# retention loop: counted vmcnt ladder (stores+atomic left in flight), vmcnt(0) before loop
# baseline (speedup 1.0000x reference)
; #define LAS __attribute__((address_space(3)))
; __device__ __forceinline__ float rms_r(float ss) { return __builtin_amdgcn_rsqf(ss * (1.0f / DM) + RMS_EPS); }
; #define LDS_BAR() do { asm volatile("s_waitcnt lgkmcnt(0)" ::: "memory"); __builtin_amdgcn_s_barrier(); asm volatile("" ::: "memory"); } while (0)
; #define RET_STAGE(Kd, Vd) do { _Pragma("unroll") for (int uu = 0; uu < 4; ++uu) { const int c8 = lc8 + 8 * uu; *(LAS u32x4*)(Ql + ls * 264 + 8 * c8) = pq[uu]; *(LAS u32x4*)((Kd) + ls * 264 + 8 * c8) = pkv[uu]; } \
;         _Pragma("unroll") for (int uu = 0; uu < 2; ++uu) { const int c8 = lc8 + 8 * uu; *(LAS u32x4*)((Vd) + ls * 136 + 8 * c8) = pv[uu]; } } while (0)
; __device__ __forceinline__ void ret_unit(LAS unsigned char* lds, bf16_t* QKV, float* gn, int b, int h, int vs, bool commit, const float* s00p, const float* ss3, bool skel = false) {
;     const int tid = threadIdx.x, lane = tid & 63, w = tid >> 6, fr = lane & 15, fq = lane >> 4;
;     LAS bf16_t* Kb = (LAS bf16_t*)lds;
;     LAS bf16_t* Ql = Kb + 2 * 64 * 264;
;     LAS bf16_t* Vb = Ql + 64 * 264;
;     LAS bf16_t* Pl = Vb + 2 * 64 * 136;
;     LAS float* st = (LAS float*)(Pl + 64 * 72);
;     const float l2g = __builtin_amdgcn_logf(1.0f - __builtin_amdgcn_exp2f(-5.0f - (float)h));
;     const float cd = __builtin_amdgcn_exp2f(64.f * l2g);
;     f32x4 state[16];
; #pragma unroll
;     for (int m = 0; m < 16; ++m) state[m] = (f32x4){0.f, 0.f, 0.f, 0.f};
;     const float s00 = s00p[b * 4 + h] * rms_r(ss3[(size_t)b * SEQ]) * rms_r(ss3[(size_t)b * SEQ]) * 0.0625f;
;     const int si = w & 3, ti0 = 2 * (w >> 2);
;     u32x4 pq[4], pkv[4], pv[2];
;     const int ls = tid & 63, lc8 = tid >> 6;
;     ...
;     RET_LOAD(0);
;     LDS_BAR();
;     RET_STAGE(Kb, Vb);
;     RET_LOAD(1);
;     if (tid < 128) st[tid] = 0.f;
;     LDS_BAR();
.LBB0_1133:
	s_ashr_i32 s58, s78, 2
	s_and_b32 s38, s78, 4
	s_and_b32 s58, s58, -8
	s_or_b32 s38, s58, s38
	s_and_b32 s79, s78, 3
	s_or_b32 s58, s38, s79
	s_ashr_i32 s59, s58, 31
	s_ashr_i32 s64, s38, 2
	s_lshl_b64 s[58:59], s[58:59], 2
	s_add_u32 s62, s3, s58
	s_addc_u32 s63, s72, s59
	s_ashr_i32 s65, s64, 31
	s_lshl_b64 s[58:59], s[64:65], 11
	s_lshl_b64 s[68:69], s[64:65], 13
	s_add_u32 s68, s33, s68
	v_mov_b32_e32 v3, s59
	v_or_b32_e32 v2, s58, v128
	s_addc_u32 s69, s70, s69
	global_load_dword v0, v133, s[62:63]
	global_load_dword v1, v133, s[68:69]
	v_lshlrev_b64 v[2:3], 13, v[2:3]
	s_lshl_b32 s62, s78, 4
	v_lshl_add_u64 v[34:35], s[26:27], 0, v[2:3]
	s_lshl_b32 s38, s79, 9
	s_lshl_b32 s68, s79, 10
	s_mov_b32 s69, s39
	s_and_b32 s62, s62, 0x180
	v_lshl_add_u64 v[2:3], v[34:35], 0, s[38:39]
	s_lshl_b32 s62, s62, 1
	s_mov_b32 s63, s39
	v_lshl_add_u64 v[34:35], v[34:35], 0, s[68:69]
	v_mov_b32_e32 v147, v133
	v_lshl_add_u64 v[34:35], v[34:35], 0, s[62:63]
	v_lshl_add_u64 v[44:45], v[34:35], 0, v[146:147]
	v_add_co_u32_e32 v34, vcc, s75, v44
	v_lshl_add_u64 v[42:43], v[2:3], 0, v[146:147]
	v_lshl_add_u64 v[38:39], v[44:45], 0, s[42:43]
	v_addc_co_u32_e32 v35, vcc, 0, v45, vcc
	s_waitcnt lgkmcnt(1)
	global_load_dwordx4 v[2:5], v[42:43], off
	s_waitcnt lgkmcnt(0)
	global_load_dwordx4 v[6:9], v[42:43], off offset:128
	global_load_dwordx4 v[10:13], v[42:43], off offset:2048
	global_load_dwordx4 v[14:17], v[42:43], off offset:2176
	global_load_dwordx4 v[18:21], v[42:43], off offset:256
	global_load_dwordx4 v[22:25], v[42:43], off offset:384
	global_load_dwordx4 v[26:29], v[42:43], off offset:2304
	global_load_dwordx4 v[30:33], v[42:43], off offset:2432
	s_nop 0
	global_load_dwordx4 v[34:37], v[34:35], off
	s_nop 0
	global_load_dwordx4 v[38:41], v[38:39], off offset:128
	s_waitcnt lgkmcnt(0)
	s_barrier
	v_lshl_add_u64 v[46:47], v[42:43], 0, s[52:53]
	v_add_co_u32_e32 v42, vcc, s76, v42
	s_nop 1
	v_addc_co_u32_e32 v43, vcc, 0, v43, vcc
	global_load_dwordx4 v[64:67], v[46:47], off offset:128
	global_load_dwordx4 v[68:71], v[46:47], off offset:256
	global_load_dwordx4 v[76:79], v[46:47], off offset:2176
	global_load_dwordx4 v[84:87], v[46:47], off offset:2304
	global_load_dwordx4 v[80:83], v[46:47], off offset:2048
	global_load_dwordx4 v[88:91], v[46:47], off offset:384
	global_load_dwordx4 v[72:75], v[42:43], off
	global_load_dwordx4 v[92:95], v[46:47], off offset:2432
	v_lshl_add_u64 v[42:43], v[44:45], 0, s[54:55]
	v_add_co_u32_e32 v44, vcc, 0x81000, v44
	s_nop 1
	v_addc_co_u32_e32 v45, vcc, 0, v45, vcc
	global_load_dwordx4 v[96:99], v[44:45], off
	global_load_dwordx4 v[100:103], v[42:43], off offset:128
	s_waitcnt vmcnt(19)
	ds_write_b128 v129, v[2:5]
	s_waitcnt vmcnt(17)
	ds_write_b128 v131, v[10:13]
	ds_write_b128 v129, v[6:9] offset:128
	s_waitcnt vmcnt(16)
	ds_write_b128 v131, v[14:17] offset:128
	s_waitcnt vmcnt(15)
	ds_write_b128 v129, v[18:21] offset:256
	s_waitcnt vmcnt(13)
	ds_write_b128 v131, v[26:29] offset:256
	ds_write_b128 v129, v[22:25] offset:384
	s_waitcnt vmcnt(12)
	ds_write_b128 v131, v[30:33] offset:384
	s_waitcnt vmcnt(11)
	ds_write_b128 v135, v[34:37]
	s_waitcnt vmcnt(10)
	ds_write_b128 v135, v[38:41] offset:128
	s_and_saveexec_b64 s[68:69], s[4:5]
	ds_write_b32 v162, v133
	s_or_b64 exec, exec, s[68:69]
	v_cvt_f32_ubyte0_e32 v2, s79
	v_sub_f32_e32 v2, 0xc0a00000, v2
	v_exp_f32_e32 v2, v2
	v_mov_b32_e32 v3, 0x358637bd
	v_fmamk_f32 v1, v1, 0x3a800000, v3
	v_rsq_f32_e32 v1, v1
	v_sub_f32_e32 v2, 1.0, v2
	v_log_f32_e32 v2, v2
	s_and_b32 s63, s77, 3
	s_lshl_b32 s68, s73, 1
	s_lshl_b32 s80, s63, 9
	v_mul_f32_e32 v2, 0x42800000, v2
	s_and_b32 s83, s68, 0x300
	v_exp_f32_e32 v150, v2
	s_lshl_b64 s[68:69], s[64:65], 24
	s_lshl_b32 s82, s63, 10
	s_or_b32 s80, s68, s80
	s_mov_b32 s81, s69
	s_lshl_b32 s63, s63, 3
	v_mul_f32_e32 v0, v0, v1
	s_waitcnt lgkmcnt(0)
	s_barrier
	v_lshl_add_u64 v[154:155], s[80:81], 0, v[140:141]
	s_or_b32 s80, s83, s82
	s_lshl_b64 s[64:65], s[64:65], 16
	v_mul_f32_e32 v0, v1, v0
	s_or_b32 s68, s68, s80
	s_or_b32 s64, s64, s63
	v_mov_b32_e32 v40, 0
	v_mul_f32_e32 v147, 0x3d800000, v0
	v_mov_b32_e32 v152, v150
	v_mov_b32_e32 v153, v150
	v_lshl_add_u64 v[156:157], s[68:69], 0, v[142:143]
	v_lshl_add_u64 v[158:159], s[64:65], 0, v[144:145]
	v_lshl_add_u64 v[160:161], s[68:69], 0, v[138:139]
	s_mov_b32 s63, 0
	v_mov_b32_e32 v41, v40
	v_mov_b32_e32 v42, v40
	v_mov_b32_e32 v43, v40
	v_mov_b32_e32 v44, v40
	v_mov_b32_e32 v45, v40
	v_mov_b32_e32 v46, v40
	v_mov_b32_e32 v47, v40
	v_mov_b32_e32 v48, v40
	v_mov_b32_e32 v49, v40
	v_mov_b32_e32 v50, v40
	v_mov_b32_e32 v51, v40
	v_mov_b32_e32 v52, v40
	v_mov_b32_e32 v53, v40
	v_mov_b32_e32 v54, v40
	v_mov_b32_e32 v55, v40
	v_mov_b32_e32 v56, v40
	v_mov_b32_e32 v57, v40
	v_mov_b32_e32 v58, v40
	v_mov_b32_e32 v59, v40
	v_mov_b32_e32 v60, v40
	v_mov_b32_e32 v61, v40
	v_mov_b32_e32 v62, v40
	v_mov_b32_e32 v63, v40
	v_mov_b32_e32 v36, v40
	v_mov_b32_e32 v37, v40
	v_mov_b32_e32 v38, v40
	v_mov_b32_e32 v39, v40
	v_mov_b32_e32 v32, v40
	v_mov_b32_e32 v33, v40
	v_mov_b32_e32 v34, v40
	v_mov_b32_e32 v35, v40
	v_mov_b32_e32 v28, v40
	v_mov_b32_e32 v29, v40
	v_mov_b32_e32 v30, v40
	v_mov_b32_e32 v31, v40
	v_mov_b32_e32 v24, v40
	v_mov_b32_e32 v25, v40
	v_mov_b32_e32 v26, v40
	v_mov_b32_e32 v27, v40
	v_mov_b32_e32 v20, v40
	v_mov_b32_e32 v21, v40
	v_mov_b32_e32 v22, v40
	v_mov_b32_e32 v23, v40
	v_mov_b32_e32 v16, v40
	v_mov_b32_e32 v17, v40
	v_mov_b32_e32 v18, v40
	v_mov_b32_e32 v19, v40
	v_mov_b32_e32 v12, v40
	v_mov_b32_e32 v13, v40
	v_mov_b32_e32 v14, v40
	v_mov_b32_e32 v15, v40
	v_mov_b32_e32 v8, v40
	v_mov_b32_e32 v9, v40
	v_mov_b32_e32 v10, v40
	v_mov_b32_e32 v11, v40
	v_mov_b32_e32 v4, v40
	v_mov_b32_e32 v5, v40
	v_mov_b32_e32 v6, v40
	v_mov_b32_e32 v7, v40
	v_mov_b32_e32 v0, v40
	v_mov_b32_e32 v1, v40
	v_mov_b32_e32 v2, v40
	v_mov_b32_e32 v3, v40
	s_waitcnt vmcnt(0)
	s_branch .LBB0_1137

; #define LAS __attribute__((address_space(3)))
; __device__ __forceinline__ u32x2 pack4(f32x4 v) { return (u32x2){pk2(v[0], v[1]), pk2(v[2], v[3])}; }
; #define SB0 __builtin_amdgcn_sched_barrier(0)
; #define SB0 __builtin_amdgcn_sched_barrier(0)
; __device__ __forceinline__ void ret_unit(LAS unsigned char* lds, bf16_t* QKV, float* gn, int b, int h, int vs, bool commit, const float* s00p, const float* ss3, bool skel = false) {
;     ...
;     for (int c = 0; c < 32; ++c) {
;         const size_t trow0 = (size_t)b * SEQ + 64 * c;
;         LAS bf16_t* Kl = Kb + (c & 1) * (64 * 264); LAS bf16_t* Vl = Vb + (c & 1) * (64 * 136);
;         LAS bf16_t* Kn = Kb + ((c & 1) ^ 1) * (64 * 264); LAS bf16_t* Vn = Vb + ((c & 1) ^ 1) * (64 * 136);
;     ...
;         f32x4 oacc[4];
; #pragma unroll
;         for (int n = 0; n < 4; ++n) oacc[n] = (f32x4){0.f, 0.f, 0.f, 0.f};
;         if (!skel) {
;         { f32x4 sv[2] = {(f32x4){0.f, 0.f, 0.f, 0.f}, (f32x4){0.f, 0.f, 0.f, 0.f}};
;           bf16x8 ka[3], qb[3][2];
;     ...
;           RA_LOAD(0); RA_LOAD(1); SB0;
; #pragma unroll
;           for (int ks = 0; ks < 8; ++ks) { if (ks + 2 < 8) RA_LOAD(ks + 2); SB0;
; #pragma unroll
;               for (int tt = 0; tt < 2; ++tt) sv[tt] = __builtin_amdgcn_mfma_f32_16x16x32_bf16(ka[ks % 3], qb[ks % 3][tt], sv[tt], 0, 0, 0);
;               SB0; }
;     ...
; #pragma unroll
;           for (int tt = 0; tt < 2; ++tt) { const int t = 16 * (ti0 + tt) + fr; f32x4 pvv;
; #pragma unroll
;               for (int r = 0; r < 4; ++r) { const int sidx = 16 * si + 4 * fq + r; pvv[r] = t >= sidx ? sv[tt][r] : 0.f; }
;               if (c == 0 && t == 0 && si == 0 && fq == 0) pvv[0] = s00;
;               *(LAS u32x2*)(Pl + t * 72 + 16 * si + 4 * fq) = pack4(pvv); } }
;         { u32x4 qf[3][4];
;     ...
;           RC_LOAD(0); RC_LOAD(1); SB0;
; #pragma unroll
;           for (int kk = 0; kk < 8; ++kk) { if (kk + 2 < 8) RC_LOAD(kk + 2);
;               const u32x2 s0 = pack4(state[2 * kk]), s1 = pack4(state[2 * kk + 1]);
;               const u32x4 aw = (u32x4){s0.x, s0.y, s1.x, s1.y}; const bf16x8 afrag = __builtin_bit_cast(bf16x8, aw);
;               SB0;
; #pragma unroll
;               for (int n = 0; n < 4; ++n) oacc[n] = __builtin_amdgcn_mfma_f32_16x16x32_bf16(afrag, __builtin_bit_cast(bf16x8, qf[kk % 3][n]), oacc[n], 0, 0, 0);
;               SB0; }
.LBB0_1137:
	s_and_b32 s65, s63, 1
	s_mul_i32 s64, s65, 0x8400
	s_add_i32 s64, s64, 0
	v_lshlrev_b32_e32 v104, 1, v164
	v_add3_u32 v149, s64, v163, v104
	ds_read_b128 v[104:107], v203
	s_waitcnt lgkmcnt(1)
	ds_read_b128 v[108:111], v203 offset:8448
	ds_read_b128 v[112:115], v149
	ds_read_b128 v[116:119], v149 offset:64
	ds_read_b128 v[120:123], v167 offset:64
	ds_read_b128 v[124:127], v168 offset:64
	ds_read_b128 v[206:209], v149 offset:128
	ds_read_b128 v[210:213], v203 offset:128
	ds_read_b128 v[214:217], v203 offset:8576
	s_waitcnt lgkmcnt(6)
	v_mfma_f32_16x16x32_bf16 v[104:107], v[112:115], v[104:107], 0
	v_mfma_f32_16x16x32_bf16 v[108:111], v[112:115], v[108:111], 0
	ds_read_b128 v[112:115], v149 offset:192
	ds_read_b128 v[218:221], v203 offset:192
	ds_read_b128 v[222:225], v203 offset:8640
	s_waitcnt lgkmcnt(7)
	v_mfma_f32_16x16x32_bf16 v[104:107], v[116:119], v[120:123], v[104:107]
	s_waitcnt lgkmcnt(6)
	v_mfma_f32_16x16x32_bf16 v[108:111], v[116:119], v[124:127], v[108:111]
	ds_read_b128 v[116:119], v149 offset:256
	ds_read_b128 v[120:123], v203 offset:256
	ds_read_b128 v[124:127], v203 offset:8704
	s_waitcnt lgkmcnt(7)
	v_mfma_f32_16x16x32_bf16 v[104:107], v[206:209], v[210:213], v[104:107]
	s_waitcnt lgkmcnt(6)
	v_mfma_f32_16x16x32_bf16 v[108:111], v[206:209], v[214:217], v[108:111]
	ds_read_b128 v[206:209], v149 offset:320
	ds_read_b128 v[210:213], v203 offset:320
	ds_read_b128 v[214:217], v203 offset:8768
	s_waitcnt lgkmcnt(7)
	v_mfma_f32_16x16x32_bf16 v[104:107], v[112:115], v[218:221], v[104:107]
	s_waitcnt lgkmcnt(6)
	v_mfma_f32_16x16x32_bf16 v[108:111], v[112:115], v[222:225], v[108:111]
	ds_read_b128 v[112:115], v149 offset:384
	ds_read_b128 v[218:221], v203 offset:384
	ds_read_b128 v[222:225], v203 offset:8832
	s_waitcnt lgkmcnt(7)
	v_mfma_f32_16x16x32_bf16 v[104:107], v[116:119], v[120:123], v[104:107]
	s_waitcnt lgkmcnt(6)
	v_mfma_f32_16x16x32_bf16 v[108:111], v[116:119], v[124:127], v[108:111]
	ds_read_b128 v[116:119], v149 offset:448
	ds_read_b128 v[120:123], v203 offset:448
	ds_read_b128 v[124:127], v203 offset:8896
	s_waitcnt lgkmcnt(7)
	v_mfma_f32_16x16x32_bf16 v[104:107], v[206:209], v[210:213], v[104:107]
	s_waitcnt lgkmcnt(6)
	v_mfma_f32_16x16x32_bf16 v[108:111], v[206:209], v[214:217], v[108:111]
	s_waitcnt lgkmcnt(4)
	v_mfma_f32_16x16x32_bf16 v[104:107], v[112:115], v[218:221], v[104:107]
	s_waitcnt lgkmcnt(3)
	v_mfma_f32_16x16x32_bf16 v[108:111], v[112:115], v[222:225], v[108:111]
	s_waitcnt lgkmcnt(1)
	v_mfma_f32_16x16x32_bf16 v[104:107], v[116:119], v[120:123], v[104:107]
	s_waitcnt lgkmcnt(0)
	v_mfma_f32_16x16x32_bf16 v[108:111], v[116:119], v[124:127], v[108:111]
	v_or_b32_e32 v112, s63, v169
	v_cmp_eq_u32_e32 vcc, 0, v112
	s_nop 3
	v_cndmask_b32_e64 v104, v104, 0, s[8:9]
	s_and_b64 vcc, vcc, s[6:7]
	v_cndmask_b32_e64 v105, 0, v105, s[10:11]
	v_cndmask_b32_e32 v104, v104, v147, vcc
	v_cndmask_b32_e64 v106, v106, 0, s[12:13]
	v_cndmask_b32_e64 v107, v107, 0, s[14:15]
	v_cvt_pk_bf16_f32 v104, v104, v105
	v_cvt_pk_bf16_f32 v105, v106, v107
	ds_write_b64 v204, v[104:105]
	v_cndmask_b32_e64 v104, v108, 0, s[16:17]
	v_cndmask_b32_e64 v105, 0, v109, s[18:19]
	v_cndmask_b32_e64 v106, v110, 0, s[20:21]
	v_cndmask_b32_e64 v107, v111, 0, s[22:23]
	v_cvt_pk_bf16_f32 v104, v104, v105
	v_cvt_pk_bf16_f32 v105, v106, v107
	ds_write_b64 v204, v[104:105] offset:2304
	ds_read2_b64 v[104:107], v170 offset1:4
	ds_read2_b64 v[108:111], v171 offset1:4
	ds_read2_b64 v[112:115], v172 offset1:4
	ds_read2_b64 v[116:119], v173 offset1:4
	ds_read2_b64 v[120:123], v170 offset0:8 offset1:12
	ds_read2_b64 v[124:127], v171 offset0:8 offset1:12
	ds_read2_b64 v[206:209], v172 offset0:8 offset1:12
	ds_read2_b64 v[210:213], v173 offset0:8 offset1:12
	ds_read2_b64 v[214:217], v174 offset1:4
	ds_read2_b64 v[218:221], v175 offset1:4
	ds_read2_b64 v[222:225], v177 offset1:4
	ds_read2_b64 v[226:229], v178 offset1:4
	v_cvt_pk_bf16_f32 v230, v60, v61
	v_cvt_pk_bf16_f32 v231, v62, v63
	v_cvt_pk_bf16_f32 v232, v56, v57
	v_cvt_pk_bf16_f32 v233, v58, v59
	s_waitcnt lgkmcnt(11)
	v_mfma_f32_16x16x32_bf16 v[104:107], v[230:233], v[104:107], 0
	s_waitcnt lgkmcnt(10)
	v_mfma_f32_16x16x32_bf16 v[108:111], v[230:233], v[108:111], 0
	s_waitcnt lgkmcnt(9)
	v_mfma_f32_16x16x32_bf16 v[112:115], v[230:233], v[112:115], 0
	s_waitcnt lgkmcnt(8)
	v_mfma_f32_16x16x32_bf16 v[116:119], v[230:233], v[116:119], 0
	ds_read2_b64 v[230:233], v179 offset1:4
	ds_read2_b64 v[234:237], v180 offset1:4
	ds_read2_b64 v[238:241], v181 offset1:4
	ds_read2_b64 v[242:245], v182 offset1:4
	v_cvt_pk_bf16_f32 v246, v52, v53
	v_cvt_pk_bf16_f32 v247, v54, v55
	v_cvt_pk_bf16_f32 v248, v48, v49
	v_cvt_pk_bf16_f32 v249, v50, v51
	s_waitcnt lgkmcnt(11)
	v_mfma_f32_16x16x32_bf16 v[104:107], v[246:249], v[120:123], v[104:107]
	s_waitcnt lgkmcnt(10)
	v_mfma_f32_16x16x32_bf16 v[108:111], v[246:249], v[124:127], v[108:111]
	s_waitcnt lgkmcnt(9)
	v_mfma_f32_16x16x32_bf16 v[112:115], v[246:249], v[206:209], v[112:115]
	s_waitcnt lgkmcnt(8)
; __device__ __forceinline__ u32x2 pack4(f32x4 v) { return (u32x2){pk2(v[0], v[1]), pk2(v[2], v[3])}; }
; #define LDS_BAR() do { asm volatile("s_waitcnt lgkmcnt(0)" ::: "memory"); __builtin_amdgcn_s_barrier(); asm volatile("" ::: "memory"); } while (0)
; #define SB0 __builtin_amdgcn_sched_barrier(0)
; #define RET_STAGE(Kd, Vd) do { _Pragma("unroll") for (int uu = 0; uu < 4; ++uu) { const int c8 = lc8 + 8 * uu; *(LAS u32x4*)(Ql + ls * 264 + 8 * c8) = pq[uu]; *(LAS u32x4*)((Kd) + ls * 264 + 8 * c8) = pkv[uu]; } \
;         _Pragma("unroll") for (int uu = 0; uu < 2; ++uu) { const int c8 = lc8 + 8 * uu; *(LAS u32x4*)((Vd) + ls * 136 + 8 * c8) = pv[uu]; } } while (0)
; #define SB0 __builtin_amdgcn_sched_barrier(0)
; #define RC_LOAD(kk_) do { _Pragma("unroll") for (int n = 0; n < 4; ++n) { const u32x2 lo = *(const LAS u32x2*)(Ql + (16 * n + fr) * 264 + 32 * (kk_) + 4 * fq), hi = *(const LAS u32x2*)(Ql + (16 * n + fr) * 264 + 32 * (kk_) + 16 + 4 * fq); \
;               qf[(kk_) % 3][n] = (u32x4){lo.x, lo.y, hi.x, hi.y}; } } while (0)
; __device__ __forceinline__ void ret_unit(LAS unsigned char* lds, bf16_t* QKV, float* gn, int b, int h, int vs, bool commit, const float* s00p, const float* ss3, bool skel = false) {
;     ...
;           for (int kk = 0; kk < 8; ++kk) { if (kk + 2 < 8) RC_LOAD(kk + 2);
;               const u32x2 s0 = pack4(state[2 * kk]), s1 = pack4(state[2 * kk + 1]);
;               const u32x4 aw = (u32x4){s0.x, s0.y, s1.x, s1.y}; const bf16x8 afrag = __builtin_bit_cast(bf16x8, aw);
;               SB0;
; #pragma unroll
;               for (int n = 0; n < 4; ++n) oacc[n] = __builtin_amdgcn_mfma_f32_16x16x32_bf16(afrag, __builtin_bit_cast(bf16x8, qf[kk % 3][n]), oacc[n], 0, 0, 0);
;               SB0; }
;     ...
;         }
; #pragma unroll
;         for (int n = 0; n < 4; ++n) oacc[n] = oacc[n] * cd;
;         }
;         LDS_BAR();
;         if (c + 1 < 32) { RET_STAGE(Kn, Vn); if (c + 2 < 32) RET_LOAD(c + 2); }
	v_mfma_f32_16x16x32_bf16 v[116:119], v[246:249], v[210:213], v[116:119]
	ds_read2_b64 v[120:123], v183 offset1:4
	ds_read2_b64 v[124:127], v184 offset1:4
	ds_read2_b64 v[206:209], v185 offset1:4
	ds_read2_b64 v[210:213], v186 offset1:4
	v_cvt_pk_bf16_f32 v246, v44, v45
	v_cvt_pk_bf16_f32 v247, v46, v47
	v_cvt_pk_bf16_f32 v248, v40, v41
	v_cvt_pk_bf16_f32 v249, v42, v43
	s_waitcnt lgkmcnt(11)
	v_mfma_f32_16x16x32_bf16 v[104:107], v[246:249], v[214:217], v[104:107]
	s_waitcnt lgkmcnt(10)
	v_mfma_f32_16x16x32_bf16 v[108:111], v[246:249], v[218:221], v[108:111]
	s_waitcnt lgkmcnt(9)
	v_mfma_f32_16x16x32_bf16 v[112:115], v[246:249], v[222:225], v[112:115]
	s_waitcnt lgkmcnt(8)
	v_mfma_f32_16x16x32_bf16 v[116:119], v[246:249], v[226:229], v[116:119]
	ds_read2_b64 v[214:217], v187 offset1:4
	ds_read2_b64 v[218:221], v188 offset1:4
	ds_read2_b64 v[222:225], v189 offset1:4
	ds_read2_b64 v[226:229], v190 offset1:4
	v_cvt_pk_bf16_f32 v246, v36, v37
	v_cvt_pk_bf16_f32 v247, v38, v39
	v_cvt_pk_bf16_f32 v248, v32, v33
	v_cvt_pk_bf16_f32 v249, v34, v35
	s_waitcnt lgkmcnt(11)
	v_mfma_f32_16x16x32_bf16 v[104:107], v[246:249], v[230:233], v[104:107]
	s_waitcnt lgkmcnt(10)
	v_mfma_f32_16x16x32_bf16 v[108:111], v[246:249], v[234:237], v[108:111]
	s_waitcnt lgkmcnt(9)
	v_mfma_f32_16x16x32_bf16 v[112:115], v[246:249], v[238:241], v[112:115]
	s_waitcnt lgkmcnt(8)
	v_mfma_f32_16x16x32_bf16 v[116:119], v[246:249], v[242:245], v[116:119]
	ds_read2_b64 v[230:233], v191 offset1:4
	ds_read2_b64 v[234:237], v192 offset1:4
	ds_read2_b64 v[238:241], v193 offset1:4
	ds_read2_b64 v[242:245], v194 offset1:4
	v_cvt_pk_bf16_f32 v246, v28, v29
	v_cvt_pk_bf16_f32 v247, v30, v31
	v_cvt_pk_bf16_f32 v248, v24, v25
	v_cvt_pk_bf16_f32 v249, v26, v27
	s_waitcnt lgkmcnt(11)
	v_mfma_f32_16x16x32_bf16 v[104:107], v[246:249], v[120:123], v[104:107]
	s_waitcnt lgkmcnt(10)
	v_mfma_f32_16x16x32_bf16 v[108:111], v[246:249], v[124:127], v[108:111]
	s_waitcnt lgkmcnt(9)
	v_mfma_f32_16x16x32_bf16 v[112:115], v[246:249], v[206:209], v[112:115]
	s_waitcnt lgkmcnt(8)
	v_mfma_f32_16x16x32_bf16 v[116:119], v[246:249], v[210:213], v[116:119]
	ds_read2_b64 v[120:123], v195 offset1:4
	ds_read2_b64 v[124:127], v196 offset1:4
	ds_read2_b64 v[206:209], v197 offset1:4
	ds_read2_b64 v[210:213], v198 offset1:4
	v_cvt_pk_bf16_f32 v246, v20, v21
	v_cvt_pk_bf16_f32 v247, v22, v23
	v_cvt_pk_bf16_f32 v248, v16, v17
	v_cvt_pk_bf16_f32 v249, v18, v19
	s_waitcnt lgkmcnt(11)
	v_mfma_f32_16x16x32_bf16 v[104:107], v[246:249], v[214:217], v[104:107]
	s_waitcnt lgkmcnt(10)
	v_mfma_f32_16x16x32_bf16 v[108:111], v[246:249], v[218:221], v[108:111]
	s_waitcnt lgkmcnt(9)
	v_mfma_f32_16x16x32_bf16 v[112:115], v[246:249], v[222:225], v[112:115]
	s_waitcnt lgkmcnt(8)
	v_mfma_f32_16x16x32_bf16 v[116:119], v[246:249], v[226:229], v[116:119]
	v_cvt_pk_bf16_f32 v214, v12, v13
	v_cvt_pk_bf16_f32 v215, v14, v15
	v_cvt_pk_bf16_f32 v216, v8, v9
	v_cvt_pk_bf16_f32 v217, v10, v11
	s_waitcnt lgkmcnt(7)
	v_mfma_f32_16x16x32_bf16 v[104:107], v[214:217], v[230:233], v[104:107]
	s_waitcnt lgkmcnt(6)
	v_mfma_f32_16x16x32_bf16 v[108:111], v[214:217], v[234:237], v[108:111]
	s_waitcnt lgkmcnt(5)
	v_mfma_f32_16x16x32_bf16 v[218:221], v[214:217], v[238:241], v[112:115]
	s_waitcnt lgkmcnt(4)
	v_mfma_f32_16x16x32_bf16 v[214:217], v[214:217], v[242:245], v[116:119]
	v_cvt_pk_bf16_f32 v222, v4, v5
	v_cvt_pk_bf16_f32 v223, v6, v7
	v_cvt_pk_bf16_f32 v224, v0, v1
	v_cvt_pk_bf16_f32 v225, v2, v3
	s_waitcnt lgkmcnt(3)
	v_mfma_f32_16x16x32_bf16 v[116:119], v[222:225], v[120:123], v[104:107]
	s_waitcnt lgkmcnt(2)
	v_mfma_f32_16x16x32_bf16 v[112:115], v[222:225], v[124:127], v[108:111]
	s_waitcnt lgkmcnt(1)
	v_mfma_f32_16x16x32_bf16 v[108:111], v[222:225], v[206:209], v[218:221]
	s_waitcnt lgkmcnt(0)
	v_mfma_f32_16x16x32_bf16 v[104:107], v[222:225], v[210:213], v[214:217]
	s_xor_b32 s68, s65, 1
	s_waitcnt lgkmcnt(0)
	s_barrier
	s_mul_i32 s69, s68, 0x8400
	s_mulk_i32 s68, 0x4400
	v_add_u32_e32 v120, s69, v131
	s_waitcnt vmcnt(7)
	ds_write_b128 v129, v[72:75]
	ds_write_b128 v120, v[80:83]
	ds_write_b128 v129, v[64:67] offset:128
	ds_write_b128 v120, v[76:79] offset:128
	ds_write_b128 v129, v[68:71] offset:256
	ds_write_b128 v120, v[84:87] offset:256
	ds_write_b128 v129, v[88:91] offset:384
	s_waitcnt vmcnt(6)
	ds_write_b128 v120, v[92:95] offset:384
	v_add_u32_e32 v120, s68, v135
	s_cmp_gt_u32 s63, 29
	s_waitcnt vmcnt(5)
	ds_write_b128 v120, v[96:99]
	s_waitcnt vmcnt(4)
	ds_write_b128 v120, v[100:103] offset:128
	s_cbranch_scc1 .LBB0_1139
	v_lshl_add_u64 v[92:93], s[50:51], 0, v[154:155]
	global_load_dwordx4 v[72:75], v[92:93], off offset:-2048
	global_load_dwordx4 v[64:67], v[92:93], off offset:-1920
	global_load_dwordx4 v[80:83], v[92:93], off
	global_load_dwordx4 v[76:79], v[92:93], off offset:128
	global_load_dwordx4 v[68:71], v[92:93], off offset:-1792
	global_load_dwordx4 v[88:91], v[92:93], off offset:-1664
	global_load_dwordx4 v[84:87], v[92:93], off offset:256
	s_nop 0
	global_load_dwordx4 v[92:95], v[92:93], off offset:384
	v_lshl_add_u64 v[96:97], s[50:51], 0, v[160:161]
	v_add_co_u32_e32 v100, vcc, 0xe301000, v96
	s_nop 1
	v_addc_co_u32_e32 v101, vcc, 0, v97, vcc
	global_load_dwordx4 v[96:99], v[100:101], off
	s_nop 0
	global_load_dwordx4 v[100:103], v[100:101], off offset:128
